# grid barrier between P2b and P3 removed: prefix waves publish a release flag, S5 mode-1 loop acquires it
# baseline (speedup 1.0000x reference)
.Lpfx_loop:
	v_lshl_add_u64 v[2:3], v[8:9], 0, s[2:3]
	global_load_dword v16, v[2:3], off offset:-2816
	global_load_dword v17, v[2:3], off offset:-2560
	global_load_dword v18, v[2:3], off offset:-2304
	global_load_dword v19, v[2:3], off offset:-2048
	global_load_dword v20, v[2:3], off offset:-1792
	global_load_dword v21, v[2:3], off offset:-1536
	global_load_dword v22, v[2:3], off offset:-1280
	global_load_dword v23, v[2:3], off offset:-1024
	global_load_dword v24, v[2:3], off offset:-768
	global_load_dword v25, v[2:3], off offset:-512
	global_load_dword v26, v[2:3], off offset:-256
	global_load_dword v27, v[2:3], off offset:0
	global_load_dword v28, v[2:3], off offset:256
	global_load_dword v29, v[2:3], off offset:512
	global_load_dword v30, v[2:3], off offset:768
	global_load_dword v31, v[2:3], off offset:1024
	global_load_dword v32, v[2:3], off offset:1280
	global_load_dword v33, v[2:3], off offset:1536
	global_load_dword v34, v[2:3], off offset:1792
	global_load_dword v35, v[2:3], off offset:2048
	global_load_dword v36, v[2:3], off offset:2304
	global_load_dword v37, v[2:3], off offset:2560
	global_load_dword v38, v[2:3], off offset:2816
	global_load_dword v39, v[2:3], off offset:3072
	s_waitcnt vmcnt(48)
	global_store_dword v[8:9], v6, off offset:-2816
	global_store_dword v[8:9], v7, off offset:-2560
	v_mul_f32_e32 v10, v1, v7
	v_mul_f32_e32 v11, v1, v6
	v_fma_f32 v12, v0, v6, -v10
	v_fma_f32 v13, v0, v7, v11
	v_add_f32_e32 v14, v12, v40
	v_add_f32_e32 v15, v13, v41
	global_store_dword v[8:9], v14, off offset:-2304
	global_store_dword v[8:9], v15, off offset:-2048
	v_mul_f32_e32 v10, v1, v15
	v_mul_f32_e32 v11, v1, v14
	v_fma_f32 v12, v0, v14, -v10
	v_fma_f32 v13, v0, v15, v11
	v_add_f32_e32 v6, v12, v42
	v_add_f32_e32 v7, v13, v43
	global_store_dword v[8:9], v6, off offset:-1792
	global_store_dword v[8:9], v7, off offset:-1536
	v_mul_f32_e32 v10, v1, v7
	v_mul_f32_e32 v11, v1, v6
	v_fma_f32 v12, v0, v6, -v10
	v_fma_f32 v13, v0, v7, v11
	v_add_f32_e32 v14, v12, v44
	v_add_f32_e32 v15, v13, v45
	global_store_dword v[8:9], v14, off offset:-1280
	global_store_dword v[8:9], v15, off offset:-1024
	v_mul_f32_e32 v10, v1, v15
	v_mul_f32_e32 v11, v1, v14
	v_fma_f32 v12, v0, v14, -v10
	v_fma_f32 v13, v0, v15, v11
	v_add_f32_e32 v6, v12, v46
	v_add_f32_e32 v7, v13, v47
	global_store_dword v[8:9], v6, off offset:-768
	global_store_dword v[8:9], v7, off offset:-512
	v_mul_f32_e32 v10, v1, v7
	v_mul_f32_e32 v11, v1, v6
	v_fma_f32 v12, v0, v6, -v10
	v_fma_f32 v13, v0, v7, v11
	v_add_f32_e32 v14, v12, v48
	v_add_f32_e32 v15, v13, v49
	global_store_dword v[8:9], v14, off offset:-256
	global_store_dword v[8:9], v15, off offset:0
	v_mul_f32_e32 v10, v1, v15
	v_mul_f32_e32 v11, v1, v14
	v_fma_f32 v12, v0, v14, -v10
	v_fma_f32 v13, v0, v15, v11
	v_add_f32_e32 v6, v12, v50
	v_add_f32_e32 v7, v13, v51
	global_store_dword v[8:9], v6, off offset:256
	global_store_dword v[8:9], v7, off offset:512
	v_mul_f32_e32 v10, v1, v7
	v_mul_f32_e32 v11, v1, v6
	v_fma_f32 v12, v0, v6, -v10
	v_fma_f32 v13, v0, v7, v11
	v_add_f32_e32 v14, v12, v52
	v_add_f32_e32 v15, v13, v53
	global_store_dword v[8:9], v14, off offset:768
	global_store_dword v[8:9], v15, off offset:1024
	v_mul_f32_e32 v10, v1, v15
	v_mul_f32_e32 v11, v1, v14
	v_fma_f32 v12, v0, v14, -v10
	v_fma_f32 v13, v0, v15, v11
	v_add_f32_e32 v6, v12, v54
	v_add_f32_e32 v7, v13, v55
	global_store_dword v[8:9], v6, off offset:1280
	global_store_dword v[8:9], v7, off offset:1536
	v_mul_f32_e32 v10, v1, v7
	v_mul_f32_e32 v11, v1, v6
	v_fma_f32 v12, v0, v6, -v10
	v_fma_f32 v13, v0, v7, v11
	v_add_f32_e32 v14, v12, v56
	v_add_f32_e32 v15, v13, v57
	global_store_dword v[8:9], v14, off offset:1792
	global_store_dword v[8:9], v15, off offset:2048
	v_mul_f32_e32 v10, v1, v15
	v_mul_f32_e32 v11, v1, v14
	v_fma_f32 v12, v0, v14, -v10
	v_fma_f32 v13, v0, v15, v11
	v_add_f32_e32 v6, v12, v58
	v_add_f32_e32 v7, v13, v59
	global_store_dword v[8:9], v6, off offset:2304
	global_store_dword v[8:9], v7, off offset:2560
	v_mul_f32_e32 v10, v1, v7
	v_mul_f32_e32 v11, v1, v6
	v_fma_f32 v12, v0, v6, -v10
	v_fma_f32 v13, v0, v7, v11
	v_add_f32_e32 v14, v12, v60
	v_add_f32_e32 v15, v13, v61
	global_store_dword v[8:9], v14, off offset:2816
	global_store_dword v[8:9], v15, off offset:3072
	v_mul_f32_e32 v10, v1, v15
	v_mul_f32_e32 v11, v1, v14
	v_fma_f32 v12, v0, v14, -v10
	v_fma_f32 v13, v0, v15, v11
	v_add_f32_e32 v6, v12, v62
	v_add_f32_e32 v7, v13, v63
	v_lshl_add_u64 v[8:9], v[2:3], 0, s[2:3]
	global_load_dword v40, v[8:9], off offset:-2816
	global_load_dword v41, v[8:9], off offset:-2560
	global_load_dword v42, v[8:9], off offset:-2304
	global_load_dword v43, v[8:9], off offset:-2048
	global_load_dword v44, v[8:9], off offset:-1792
	global_load_dword v45, v[8:9], off offset:-1536
	global_load_dword v46, v[8:9], off offset:-1280
	global_load_dword v47, v[8:9], off offset:-1024
	global_load_dword v48, v[8:9], off offset:-768
	global_load_dword v49, v[8:9], off offset:-512
	global_load_dword v50, v[8:9], off offset:-256
	global_load_dword v51, v[8:9], off offset:0
	global_load_dword v52, v[8:9], off offset:256
	global_load_dword v53, v[8:9], off offset:512
	global_load_dword v54, v[8:9], off offset:768
	global_load_dword v55, v[8:9], off offset:1024
	global_load_dword v56, v[8:9], off offset:1280
	global_load_dword v57, v[8:9], off offset:1536
	global_load_dword v58, v[8:9], off offset:1792
	global_load_dword v59, v[8:9], off offset:2048
	global_load_dword v60, v[8:9], off offset:2304
	global_load_dword v61, v[8:9], off offset:2560
	global_load_dword v62, v[8:9], off offset:2816
	global_load_dword v63, v[8:9], off offset:3072
	s_waitcnt vmcnt(48)
	global_store_dword v[2:3], v6, off offset:-2816
	global_store_dword v[2:3], v7, off offset:-2560
	v_mul_f32_e32 v10, v1, v7
	v_mul_f32_e32 v11, v1, v6
	v_fma_f32 v12, v0, v6, -v10
	v_fma_f32 v13, v0, v7, v11
	v_add_f32_e32 v14, v12, v16
	v_add_f32_e32 v15, v13, v17
	global_store_dword v[2:3], v14, off offset:-2304
	global_store_dword v[2:3], v15, off offset:-2048
	v_mul_f32_e32 v10, v1, v15
	v_mul_f32_e32 v11, v1, v14
	v_fma_f32 v12, v0, v14, -v10
	v_fma_f32 v13, v0, v15, v11
	v_add_f32_e32 v6, v12, v18
	v_add_f32_e32 v7, v13, v19
	global_store_dword v[2:3], v6, off offset:-1792
	global_store_dword v[2:3], v7, off offset:-1536
	v_mul_f32_e32 v10, v1, v7
	v_mul_f32_e32 v11, v1, v6
	v_fma_f32 v12, v0, v6, -v10
	v_fma_f32 v13, v0, v7, v11
	v_add_f32_e32 v14, v12, v20
	v_add_f32_e32 v15, v13, v21
	global_store_dword v[2:3], v14, off offset:-1280
	global_store_dword v[2:3], v15, off offset:-1024
	v_mul_f32_e32 v10, v1, v15
	v_mul_f32_e32 v11, v1, v14
	v_fma_f32 v12, v0, v14, -v10
	v_fma_f32 v13, v0, v15, v11
	v_add_f32_e32 v6, v12, v22
	v_add_f32_e32 v7, v13, v23
	global_store_dword v[2:3], v6, off offset:-768
	global_store_dword v[2:3], v7, off offset:-512
	v_mul_f32_e32 v10, v1, v7
	v_mul_f32_e32 v11, v1, v6
	v_fma_f32 v12, v0, v6, -v10
	v_fma_f32 v13, v0, v7, v11
	v_add_f32_e32 v14, v12, v24
	v_add_f32_e32 v15, v13, v25
	global_store_dword v[2:3], v14, off offset:-256
	global_store_dword v[2:3], v15, off offset:0
	v_mul_f32_e32 v10, v1, v15
	v_mul_f32_e32 v11, v1, v14
	v_fma_f32 v12, v0, v14, -v10
	v_fma_f32 v13, v0, v15, v11
	v_add_f32_e32 v6, v12, v26
	v_add_f32_e32 v7, v13, v27
	global_store_dword v[2:3], v6, off offset:256
	global_store_dword v[2:3], v7, off offset:512
	v_mul_f32_e32 v10, v1, v7
	v_mul_f32_e32 v11, v1, v6
	v_fma_f32 v12, v0, v6, -v10
	v_fma_f32 v13, v0, v7, v11
	v_add_f32_e32 v14, v12, v28
	v_add_f32_e32 v15, v13, v29
	global_store_dword v[2:3], v14, off offset:768
	global_store_dword v[2:3], v15, off offset:1024
	v_mul_f32_e32 v10, v1, v15
	v_mul_f32_e32 v11, v1, v14
	v_fma_f32 v12, v0, v14, -v10
	v_fma_f32 v13, v0, v15, v11
	v_add_f32_e32 v6, v12, v30
	v_add_f32_e32 v7, v13, v31
	global_store_dword v[2:3], v6, off offset:1280
	global_store_dword v[2:3], v7, off offset:1536
	v_mul_f32_e32 v10, v1, v7
	v_mul_f32_e32 v11, v1, v6
	v_fma_f32 v12, v0, v6, -v10
	v_fma_f32 v13, v0, v7, v11
	v_add_f32_e32 v14, v12, v32
	v_add_f32_e32 v15, v13, v33
	global_store_dword v[2:3], v14, off offset:1792
	global_store_dword v[2:3], v15, off offset:2048
	v_mul_f32_e32 v10, v1, v15
	v_mul_f32_e32 v11, v1, v14
	v_fma_f32 v12, v0, v14, -v10
	v_fma_f32 v13, v0, v15, v11
	v_add_f32_e32 v6, v12, v34
	v_add_f32_e32 v7, v13, v35
	global_store_dword v[2:3], v6, off offset:2304
	global_store_dword v[2:3], v7, off offset:2560
	v_mul_f32_e32 v10, v1, v7
	v_mul_f32_e32 v11, v1, v6
	v_fma_f32 v12, v0, v6, -v10
	v_fma_f32 v13, v0, v7, v11
	v_add_f32_e32 v14, v12, v36
	v_add_f32_e32 v15, v13, v37
	global_store_dword v[2:3], v14, off offset:2816
	global_store_dword v[2:3], v15, off offset:3072
	v_mul_f32_e32 v10, v1, v15
	v_mul_f32_e32 v11, v1, v14
	v_fma_f32 v12, v0, v14, -v10
	v_fma_f32 v13, v0, v15, v11
	v_add_f32_e32 v6, v12, v38
	v_add_f32_e32 v7, v13, v39
	s_add_i32 s4, s4, -1
	s_cmp_lg_u32 s4, 0
	s_cbranch_scc1 .Lpfx_loop
	v_lshl_add_u64 v[2:3], v[8:9], 0, s[2:3]
	global_load_dword v16, v[2:3], off offset:-2816
	global_load_dword v17, v[2:3], off offset:-2560
	global_load_dword v18, v[2:3], off offset:-2304
	global_load_dword v19, v[2:3], off offset:-2048
	global_load_dword v20, v[2:3], off offset:-1792
	global_load_dword v21, v[2:3], off offset:-1536
	global_load_dword v22, v[2:3], off offset:-1280
	global_load_dword v23, v[2:3], off offset:-1024
	global_load_dword v24, v[2:3], off offset:-768
	global_load_dword v25, v[2:3], off offset:-512
	global_load_dword v26, v[2:3], off offset:-256
	global_load_dword v27, v[2:3], off offset:0
	global_load_dword v28, v[2:3], off offset:256
	global_load_dword v29, v[2:3], off offset:512
	global_load_dword v30, v[2:3], off offset:768
	global_load_dword v31, v[2:3], off offset:1024
	global_load_dword v32, v[2:3], off offset:1280
	global_load_dword v33, v[2:3], off offset:1536
	global_load_dword v34, v[2:3], off offset:1792
	global_load_dword v35, v[2:3], off offset:2048
	global_load_dword v36, v[2:3], off offset:2304
	global_load_dword v37, v[2:3], off offset:2560
	global_load_dword v38, v[2:3], off offset:2816
	global_load_dword v39, v[2:3], off offset:3072
	s_waitcnt vmcnt(48)
	global_store_dword v[8:9], v6, off offset:-2816
	global_store_dword v[8:9], v7, off offset:-2560
	v_mul_f32_e32 v10, v1, v7
	v_mul_f32_e32 v11, v1, v6
	v_fma_f32 v12, v0, v6, -v10
	v_fma_f32 v13, v0, v7, v11
	v_add_f32_e32 v14, v12, v40
	v_add_f32_e32 v15, v13, v41
	global_store_dword v[8:9], v14, off offset:-2304
	global_store_dword v[8:9], v15, off offset:-2048
	v_mul_f32_e32 v10, v1, v15
	v_mul_f32_e32 v11, v1, v14
	v_fma_f32 v12, v0, v14, -v10
	v_fma_f32 v13, v0, v15, v11
	v_add_f32_e32 v6, v12, v42
	v_add_f32_e32 v7, v13, v43
	global_store_dword v[8:9], v6, off offset:-1792
	global_store_dword v[8:9], v7, off offset:-1536
	v_mul_f32_e32 v10, v1, v7
	v_mul_f32_e32 v11, v1, v6
	v_fma_f32 v12, v0, v6, -v10
	v_fma_f32 v13, v0, v7, v11
	v_add_f32_e32 v14, v12, v44
	v_add_f32_e32 v15, v13, v45
	global_store_dword v[8:9], v14, off offset:-1280
	global_store_dword v[8:9], v15, off offset:-1024
	v_mul_f32_e32 v10, v1, v15
	v_mul_f32_e32 v11, v1, v14
	v_fma_f32 v12, v0, v14, -v10
	v_fma_f32 v13, v0, v15, v11
	v_add_f32_e32 v6, v12, v46
	v_add_f32_e32 v7, v13, v47
	global_store_dword v[8:9], v6, off offset:-768
	global_store_dword v[8:9], v7, off offset:-512
	v_mul_f32_e32 v10, v1, v7
	v_mul_f32_e32 v11, v1, v6
	v_fma_f32 v12, v0, v6, -v10
	v_fma_f32 v13, v0, v7, v11
	v_add_f32_e32 v14, v12, v48
	v_add_f32_e32 v15, v13, v49
	global_store_dword v[8:9], v14, off offset:-256
	global_store_dword v[8:9], v15, off offset:0
	v_mul_f32_e32 v10, v1, v15
	v_mul_f32_e32 v11, v1, v14
	v_fma_f32 v12, v0, v14, -v10
	v_fma_f32 v13, v0, v15, v11
	v_add_f32_e32 v6, v12, v50
	v_add_f32_e32 v7, v13, v51
	global_store_dword v[8:9], v6, off offset:256
	global_store_dword v[8:9], v7, off offset:512
	v_mul_f32_e32 v10, v1, v7
	v_mul_f32_e32 v11, v1, v6
	v_fma_f32 v12, v0, v6, -v10
	v_fma_f32 v13, v0, v7, v11
	v_add_f32_e32 v14, v12, v52
	v_add_f32_e32 v15, v13, v53
	global_store_dword v[8:9], v14, off offset:768
	global_store_dword v[8:9], v15, off offset:1024
	v_mul_f32_e32 v10, v1, v15
	v_mul_f32_e32 v11, v1, v14
	v_fma_f32 v12, v0, v14, -v10
	v_fma_f32 v13, v0, v15, v11
	v_add_f32_e32 v6, v12, v54
	v_add_f32_e32 v7, v13, v55
	global_store_dword v[8:9], v6, off offset:1280
	global_store_dword v[8:9], v7, off offset:1536
	v_mul_f32_e32 v10, v1, v7
	v_mul_f32_e32 v11, v1, v6
	v_fma_f32 v12, v0, v6, -v10
	v_fma_f32 v13, v0, v7, v11
	v_add_f32_e32 v14, v12, v56
	v_add_f32_e32 v15, v13, v57
	global_store_dword v[8:9], v14, off offset:1792
	global_store_dword v[8:9], v15, off offset:2048
	v_mul_f32_e32 v10, v1, v15
	v_mul_f32_e32 v11, v1, v14
	v_fma_f32 v12, v0, v14, -v10
	v_fma_f32 v13, v0, v15, v11
	v_add_f32_e32 v6, v12, v58
	v_add_f32_e32 v7, v13, v59
	global_store_dword v[8:9], v6, off offset:2304
	global_store_dword v[8:9], v7, off offset:2560
	v_mul_f32_e32 v10, v1, v7
	v_mul_f32_e32 v11, v1, v6
	v_fma_f32 v12, v0, v6, -v10
	v_fma_f32 v13, v0, v7, v11
	v_add_f32_e32 v14, v12, v60
	v_add_f32_e32 v15, v13, v61
	global_store_dword v[8:9], v14, off offset:2816
	global_store_dword v[8:9], v15, off offset:3072
	v_mul_f32_e32 v10, v1, v15
	v_mul_f32_e32 v11, v1, v14
	v_fma_f32 v12, v0, v14, -v10
	v_fma_f32 v13, v0, v15, v11
	v_add_f32_e32 v6, v12, v62
	v_add_f32_e32 v7, v13, v63
	s_waitcnt vmcnt(24)
	global_store_dword v[2:3], v6, off offset:-2816
	global_store_dword v[2:3], v7, off offset:-2560
	v_mul_f32_e32 v10, v1, v7
	v_mul_f32_e32 v11, v1, v6
	v_fma_f32 v12, v0, v6, -v10
	v_fma_f32 v13, v0, v7, v11
	v_add_f32_e32 v14, v12, v16
	v_add_f32_e32 v15, v13, v17
	global_store_dword v[2:3], v14, off offset:-2304
	global_store_dword v[2:3], v15, off offset:-2048
	v_mul_f32_e32 v10, v1, v15
	v_mul_f32_e32 v11, v1, v14
	v_fma_f32 v12, v0, v14, -v10
	v_fma_f32 v13, v0, v15, v11
	v_add_f32_e32 v6, v12, v18
	v_add_f32_e32 v7, v13, v19
	global_store_dword v[2:3], v6, off offset:-1792
	global_store_dword v[2:3], v7, off offset:-1536
	v_mul_f32_e32 v10, v1, v7
	v_mul_f32_e32 v11, v1, v6
	v_fma_f32 v12, v0, v6, -v10
	v_fma_f32 v13, v0, v7, v11
	v_add_f32_e32 v14, v12, v20
	v_add_f32_e32 v15, v13, v21
	global_store_dword v[2:3], v14, off offset:-1280
	global_store_dword v[2:3], v15, off offset:-1024
	v_mul_f32_e32 v10, v1, v15
	v_mul_f32_e32 v11, v1, v14
	v_fma_f32 v12, v0, v14, -v10
	v_fma_f32 v13, v0, v15, v11
	v_add_f32_e32 v6, v12, v22
	v_add_f32_e32 v7, v13, v23
	global_store_dword v[2:3], v6, off offset:-768
	global_store_dword v[2:3], v7, off offset:-512
	v_mul_f32_e32 v10, v1, v7
	v_mul_f32_e32 v11, v1, v6
	v_fma_f32 v12, v0, v6, -v10
	v_fma_f32 v13, v0, v7, v11
	v_add_f32_e32 v14, v12, v24
	v_add_f32_e32 v15, v13, v25
	global_store_dword v[2:3], v14, off offset:-256
	global_store_dword v[2:3], v15, off offset:0
	v_mul_f32_e32 v10, v1, v15
	v_mul_f32_e32 v11, v1, v14
	v_fma_f32 v12, v0, v14, -v10
	v_fma_f32 v13, v0, v15, v11
	v_add_f32_e32 v6, v12, v26
	v_add_f32_e32 v7, v13, v27
	global_store_dword v[2:3], v6, off offset:256
	global_store_dword v[2:3], v7, off offset:512
	v_mul_f32_e32 v10, v1, v7
	v_mul_f32_e32 v11, v1, v6
	v_fma_f32 v12, v0, v6, -v10
	v_fma_f32 v13, v0, v7, v11
	v_add_f32_e32 v14, v12, v28
	v_add_f32_e32 v15, v13, v29
	global_store_dword v[2:3], v14, off offset:768
	global_store_dword v[2:3], v15, off offset:1024
	v_mul_f32_e32 v10, v1, v15
	v_mul_f32_e32 v11, v1, v14
	v_fma_f32 v12, v0, v14, -v10
	v_fma_f32 v13, v0, v15, v11
	v_add_f32_e32 v6, v12, v30
	v_add_f32_e32 v7, v13, v31
	global_store_dword v[2:3], v6, off offset:1280
	global_store_dword v[2:3], v7, off offset:1536
	v_mul_f32_e32 v10, v1, v7
	v_mul_f32_e32 v11, v1, v6
	v_fma_f32 v12, v0, v6, -v10
	v_fma_f32 v13, v0, v7, v11
	v_add_f32_e32 v14, v12, v32
	v_add_f32_e32 v15, v13, v33
	global_store_dword v[2:3], v14, off offset:1792
	global_store_dword v[2:3], v15, off offset:2048
	v_mul_f32_e32 v10, v1, v15
	v_mul_f32_e32 v11, v1, v14
	v_fma_f32 v12, v0, v14, -v10
	v_fma_f32 v13, v0, v15, v11
	v_add_f32_e32 v6, v12, v34
	v_add_f32_e32 v7, v13, v35
	global_store_dword v[2:3], v6, off offset:2304
	global_store_dword v[2:3], v7, off offset:2560
	v_mul_f32_e32 v10, v1, v7
	v_mul_f32_e32 v11, v1, v6
	v_fma_f32 v12, v0, v6, -v10
	v_fma_f32 v13, v0, v7, v11
	v_add_f32_e32 v14, v12, v36
	v_add_f32_e32 v15, v13, v37
	global_store_dword v[2:3], v14, off offset:2816
	global_store_dword v[2:3], v15, off offset:3072
	v_mul_f32_e32 v10, v1, v15
	v_mul_f32_e32 v11, v1, v14
	v_fma_f32 v12, v0, v14, -v10
	v_fma_f32 v13, v0, v15, v11
	v_add_f32_e32 v6, v12, v38
	v_add_f32_e32 v7, v13, v39
	s_waitcnt vmcnt(0)
	buffer_wbl2 sc1
	s_waitcnt vmcnt(0)
	v_readlane_b32 s10, v253, 2
	v_readlane_b32 s11, v253, 3
	s_lshl_b32 s12, s45, 8
	s_add_i32 s12, s12, 0xc2820
	s_add_u32 s10, s10, s12
	s_addc_u32 s11, s11, 0
	s_mov_b64 s[12:13], exec
	s_mov_b64 exec, 1
	v_mov_b32_e32 v10, 1
	v_mov_b32_e32 v11, 0
	s_nop 3
	global_atomic_add v11, v10, s[10:11]
	s_mov_b64 exec, s[12:13]
	.p2align 6
.LBB0_441:
	s_or_b64 exec, exec, s[0:1]
	s_waitcnt vmcnt(0)
	s_waitcnt lgkmcnt(0)
	s_barrier
	s_mov_b64 s[30:31], exec
	v_readlane_b32 s0, v253, 6
	v_readlane_b32 s1, v253, 7
	s_and_b64 s[0:1], s[30:31], s[0:1]
	s_mov_b64 exec, s[0:1]
	s_branch .LBB0_485
	v_readlane_b32 s34, v254, 3
	v_readlane_b32 s0, v254, 61
	v_readlane_b32 s35, v254, 4
	s_mov_b32 s33, s70
	v_mov_b32_e32 v0, s0
	s_waitcnt vmcnt(0) expcnt(0) lgkmcnt(0)
	ds_read_b32 v2, v0
	v_readlane_b32 s0, v254, 62
	s_waitcnt lgkmcnt(0)
	v_cmp_ne_u32_e32 vcc, 0, v2
	v_mov_b32_e32 v0, s0
	ds_read_b32 v0, v0
	s_cbranch_vccnz .LBB0_456
	s_add_u32 s0, s34, 0x1000
	s_addc_u32 s1, s35, 0
	s_add_u32 s2, s34, 0x1100
	s_addc_u32 s3, s35, 0
	s_add_u32 s4, s34, 0x1200
	s_addc_u32 s5, s35, 0
	s_add_u32 s6, s34, 0x1300
	s_addc_u32 s7, s35, 0
	s_mov_b32 s26, 1
	s_mov_b64 s[8:9], 0
	s_branch .LBB0_446

.LBB0_637:
	v_readlane_b32 s0, v253, 0
	v_readlane_b32 s1, v253, 1
	v_readlane_b32 s2, v253, 2
	v_readlane_b32 s3, v253, 3
	v_mov_b32_e32 v0, v170
	s_mov_b64 s[0:1], s[2:3]
	s_and_b64 s[0:1], s[78:79], exec
	v_ashrrev_i32_e32 v0, 6, v0
	s_movk_i32 s0, 0x84
	s_cselect_b32 s16, 0x80, s0
	v_add_u32_e32 v1, s71, v0
	s_lshr_b32 s29, s71, 3
	s_and_b32 s29, s29, 7
	s_lshr_b32 s28, s71, 6
	s_lshl_b32 s28, s28, 6
	s_add_i32 s28, s28, s29
	v_lshl_add_u32 v105, v0, 3, s28
	s_lshl_b32 s17, s16, 6
	v_cmp_gt_i32_e32 vcc, s17, v105
	s_and_saveexec_b64 s[0:1], vcc
	s_cbranch_execz .LBB0_654
	v_cvt_f32_u32_e32 v1, s16
	s_movk_i32 s2, 0x4a00
	v_mul_lo_u32 v0, v0, s2
	v_readlane_b32 s2, v255, 39
	v_rcp_iflag_f32_e32 v1, v1
	s_lshl_b32 s18, s2, 6
	s_lshl_b32 s19, s2, 9
	s_sub_i32 s2, 0, s16
	v_mul_f32_e32 v1, 0x4f7ffffe, v1
	v_cvt_u32_f32_e32 v1, v1
	v_add_u32_e32 v194, 0, v0
	s_mov_b64 s[6:7], 0
	v_mul_lo_u32 v0, s2, v1
	v_mul_hi_u32 v0, v1, v0
	v_add_u32_e32 v195, v1, v0
	v_readlane_b32 s24, v253, 2
	v_readlane_b32 s25, v253, 3
	v_readlane_b32 s28, v255, 39
	s_lshr_b32 s29, s71, 3
	s_and_b32 s29, s29, 7
	s_lshl_b32 s28, s28, 3
	s_add_i32 s28, s28, s29
	s_lshr_b32 s26, s28, 1
	s_lshl_b32 s26, s26, 8
	s_and_b32 s27, s28, 1
	s_lshl_b32 s27, s27, 7
	s_add_i32 s26, s26, s27
	s_add_i32 s26, s26, 0xc0040
	s_add_u32 s24, s24, s26
	s_addc_u32 s25, s25, 0
	v_readlane_b32 s26, v253, 2
	v_readlane_b32 s27, v253, 3
	v_readlane_b32 s30, v255, 39
	s_nop 1
	s_lshl_b32 s30, s30, 8
	s_add_i32 s30, s30, 0xc2820
	s_add_u32 s26, s26, s30
	s_addc_u32 s27, s27, 0
	s_movk_i32 s31, 0
	v_mov_b32_e32 v185, 0
	s_nop 1
.Lpfxw_loop:
	global_load_dword v184, v185, s[26:27] sc1
	s_waitcnt vmcnt(0)
	v_readfirstlane_b32 s30, v184
	s_cmp_ge_u32 s30, 0x80
	s_cbranch_scc1 .Lpfxw_done
	s_sleep 1
	s_add_i32 s31, s31, 1
	s_cmp_lt_u32 s31, 0x800
	s_cbranch_scc1 .Lpfxw_loop
.Lpfxw_done:
	buffer_inv sc1
	s_branch .LBB0_640
